# v29: v22 plus paired 64-bit moves for accumulator re-zeroing between GEMM units
# speedup vs baseline: 1.0209x; 1.0035x over previous
.LBB0_277:
	s_ashr_i32 s23, s22, 31
	s_lshl_b64 s[0:1], s[22:23], 19
	v_cmp_lt_i64_e32 vcc, s[24:25], v[150:151]
	s_add_u32 s24, s5, s0
	s_addc_u32 s25, s38, s1
	s_and_b64 s[0:1], vcc, exec
	s_cselect_b32 s23, s25, s35
	s_cselect_b32 s56, s24, s34
	s_ashr_i32 s21, s20, 31
	s_lshl_b64 s[0:1], s[20:21], 19
	s_add_u32 s26, s39, s0
	s_addc_u32 s27, s40, s1
	s_and_b64 s[0:1], vcc, exec
	s_cselect_b32 s21, s27, s31
	s_cselect_b32 s57, s26, s30
	s_add_u32 s58, s30, 0x100
	s_addc_u32 s59, s31, 0
	s_add_u32 s30, s34, 0x40080
	v_mov_b64_e32 v[2:3], 0
	v_mov_b64_e32 v[4:5], 0
	v_mov_b64_e32 v[6:7], 0
	v_mov_b64_e32 v[8:9], 0
	v_mov_b64_e32 v[10:11], 0
	v_mov_b64_e32 v[12:13], 0
	v_mov_b64_e32 v[14:15], 0
	v_mov_b64_e32 v[16:17], 0
	v_mov_b64_e32 v[18:19], 0
	v_mov_b64_e32 v[20:21], 0
	v_mov_b64_e32 v[22:23], 0
	v_mov_b64_e32 v[24:25], 0
	v_mov_b64_e32 v[26:27], 0
	v_mov_b64_e32 v[28:29], 0
	v_mov_b64_e32 v[30:31], 0
	v_mov_b64_e32 v[32:33], 0
	v_mov_b64_e32 v[34:35], 0
	v_mov_b64_e32 v[36:37], 0
	v_mov_b64_e32 v[38:39], 0
	v_mov_b64_e32 v[40:41], 0
	v_mov_b64_e32 v[42:43], 0
	v_mov_b64_e32 v[44:45], 0
	v_mov_b64_e32 v[46:47], 0
	v_mov_b64_e32 v[48:49], 0
	v_mov_b64_e32 v[50:51], 0
	v_mov_b64_e32 v[52:53], 0
	v_mov_b64_e32 v[54:55], 0
	v_mov_b64_e32 v[56:57], 0
	v_mov_b64_e32 v[58:59], 0
	v_mov_b64_e32 v[60:61], 0
	v_mov_b64_e32 v[62:63], 0
	v_mov_b64_e32 v[64:65], 0
	v_mov_b64_e32 v[66:67], 0
	v_mov_b64_e32 v[68:69], 0
	v_mov_b64_e32 v[70:71], 0
	v_mov_b64_e32 v[72:73], 0
	v_mov_b64_e32 v[74:75], 0
	v_mov_b64_e32 v[76:77], 0
	v_mov_b64_e32 v[78:79], 0
	v_mov_b64_e32 v[80:81], 0
	v_mov_b64_e32 v[82:83], 0
	v_mov_b64_e32 v[84:85], 0
	v_mov_b64_e32 v[86:87], 0
	v_mov_b64_e32 v[88:89], 0
	v_mov_b64_e32 v[90:91], 0
	v_mov_b64_e32 v[92:93], 0
	v_mov_b64_e32 v[94:95], 0
	v_mov_b64_e32 v[96:97], 0
	v_mov_b64_e32 v[98:99], 0
	v_mov_b64_e32 v[100:101], 0
	v_mov_b64_e32 v[102:103], 0
	v_mov_b64_e32 v[104:105], 0
	v_mov_b64_e32 v[106:107], 0
	v_mov_b64_e32 v[108:109], 0
	v_mov_b64_e32 v[110:111], 0
	v_mov_b64_e32 v[112:113], 0
	v_mov_b64_e32 v[114:115], 0
	v_mov_b64_e32 v[116:117], 0
	v_mov_b64_e32 v[118:119], 0
	v_mov_b64_e32 v[120:121], 0
	v_mov_b64_e32 v[122:123], 0
	v_mov_b64_e32 v[124:125], 0
	v_mov_b64_e32 v[126:127], 0
	v_mov_b64_e32 v[128:129], 0
	s_addc_u32 s31, s35, 0
	s_mov_b32 s60, -2

.LBB0_433:
	s_add_i32 s55, s55, 1
	s_mov_b64 s[0:1], s[14:15]
	s_lshr_b32 s14, s55, 2
	s_mul_i32 s14, s14, s74
	s_mov_b64 s[36:37], s[34:35]
	s_mov_b32 s35, s56
	s_add_i32 s56, s14, s2
	s_cmpk_lt_i32 s56, 0x100
	s_cselect_b64 s[38:39], -1, 0
	s_cmpk_gt_i32 s56, 0xff
	s_mov_b32 s34, s57
	s_cselect_b64 s[30:31], -1, 0
	s_and_b32 s57, s55, 3
	s_and_b64 s[14:15], s[38:39], exec
	s_cselect_b32 s14, s56, s35
	s_cselect_b32 s34, s57, s34
	s_ashr_i32 s15, s14, 31
	s_lshl_b64 s[14:15], s[14:15], 19
	s_add_u32 s14, s20, s14
	s_addc_u32 s15, s21, s15
	s_and_b64 s[40:41], s[38:39], exec
	s_cselect_b32 s60, s15, s1
	s_cselect_b32 s61, s14, s0
	s_ashr_i32 s35, s34, 31
	s_lshl_b64 s[34:35], s[34:35], 19
	s_add_u32 s34, s8, s34
	s_addc_u32 s35, s9, s35
	s_and_b64 s[38:39], s[38:39], exec
	s_cselect_b32 s62, s35, s37
	s_cselect_b32 s63, s34, s36
	s_add_u32 s66, s36, 0x100
	s_addc_u32 s67, s37, 0
	s_add_u32 s36, s0, 0x40080
	v_mov_b64_e32 v[2:3], 0
	v_mov_b64_e32 v[4:5], 0
	v_mov_b64_e32 v[6:7], 0
	v_mov_b64_e32 v[8:9], 0
	v_mov_b64_e32 v[10:11], 0
	v_mov_b64_e32 v[12:13], 0
	v_mov_b64_e32 v[14:15], 0
	v_mov_b64_e32 v[16:17], 0
	v_mov_b64_e32 v[18:19], 0
	v_mov_b64_e32 v[20:21], 0
	v_mov_b64_e32 v[22:23], 0
	v_mov_b64_e32 v[24:25], 0
	v_mov_b64_e32 v[26:27], 0
	v_mov_b64_e32 v[28:29], 0
	v_mov_b64_e32 v[30:31], 0
	v_mov_b64_e32 v[32:33], 0
	v_mov_b64_e32 v[34:35], 0
	v_mov_b64_e32 v[36:37], 0
	v_mov_b64_e32 v[38:39], 0
	v_mov_b64_e32 v[40:41], 0
	v_mov_b64_e32 v[42:43], 0
	v_mov_b64_e32 v[44:45], 0
	v_mov_b64_e32 v[46:47], 0
	v_mov_b64_e32 v[48:49], 0
	v_mov_b64_e32 v[50:51], 0
	v_mov_b64_e32 v[52:53], 0
	v_mov_b64_e32 v[54:55], 0
	v_mov_b64_e32 v[56:57], 0
	v_mov_b64_e32 v[58:59], 0
	v_mov_b64_e32 v[60:61], 0
	v_mov_b64_e32 v[62:63], 0
	v_mov_b64_e32 v[64:65], 0
	v_mov_b64_e32 v[66:67], 0
	v_mov_b64_e32 v[68:69], 0
	v_mov_b64_e32 v[70:71], 0
	v_mov_b64_e32 v[72:73], 0
	v_mov_b64_e32 v[74:75], 0
	v_mov_b64_e32 v[76:77], 0
	v_mov_b64_e32 v[78:79], 0
	v_mov_b64_e32 v[80:81], 0
	v_mov_b64_e32 v[82:83], 0
	v_mov_b64_e32 v[84:85], 0
	v_mov_b64_e32 v[86:87], 0
	v_mov_b64_e32 v[88:89], 0
	v_mov_b64_e32 v[90:91], 0
	v_mov_b64_e32 v[92:93], 0
	v_mov_b64_e32 v[94:95], 0
	v_mov_b64_e32 v[96:97], 0
	v_mov_b64_e32 v[98:99], 0
	v_mov_b64_e32 v[100:101], 0
	v_mov_b64_e32 v[102:103], 0
	v_mov_b64_e32 v[104:105], 0
	v_mov_b64_e32 v[106:107], 0
	v_mov_b64_e32 v[108:109], 0
	v_mov_b64_e32 v[110:111], 0
	v_mov_b64_e32 v[112:113], 0
	v_mov_b64_e32 v[114:115], 0
	v_mov_b64_e32 v[116:117], 0
	v_mov_b64_e32 v[118:119], 0
	v_mov_b64_e32 v[120:121], 0
	v_mov_b64_e32 v[122:123], 0
	v_mov_b64_e32 v[124:125], 0
	v_mov_b64_e32 v[126:127], 0
	v_mov_b64_e32 v[128:129], 0
	s_addc_u32 s37, s1, 0
	s_mov_b32 s69, -2
	s_waitcnt vmcnt(0)

.LBB0_687:
	s_ashr_i32 s0, s54, 5
	s_ashr_i32 s1, s0, 31
	s_lshl_b64 s[0:1], s[0:1], 21
	s_add_u32 s12, s4, s0
	s_addc_u32 s13, s5, s1
	s_ashr_i32 s25, s24, 31
	s_lshl_b64 s[0:1], s[24:25], 18
	s_add_u32 s12, s12, s0
	s_addc_u32 s13, s13, s1
	s_and_b64 s[0:1], s[10:11], exec
	s_cselect_b32 s25, s13, s31
	s_cselect_b32 s27, s12, s30
	v_mov_b32_e32 v173, v163
	v_mov_b32_e32 v175, v163
	s_add_u32 s29, s30, 0x100
	v_mov_b64_e32 v[34:35], 0
	v_mov_b64_e32 v[36:37], 0
	v_mov_b64_e32 v[38:39], 0
	v_mov_b64_e32 v[40:41], 0
	v_mov_b64_e32 v[42:43], 0
	v_mov_b64_e32 v[44:45], 0
	v_mov_b64_e32 v[46:47], 0
	v_mov_b64_e32 v[48:49], 0
	v_mov_b64_e32 v[50:51], 0
	v_mov_b64_e32 v[52:53], 0
	v_mov_b64_e32 v[54:55], 0
	v_mov_b64_e32 v[56:57], 0
	v_mov_b64_e32 v[58:59], 0
	v_mov_b64_e32 v[60:61], 0
	v_mov_b64_e32 v[62:63], 0
	v_mov_b64_e32 v[64:65], 0
	v_mov_b64_e32 v[66:67], 0
	v_mov_b64_e32 v[68:69], 0
	v_mov_b64_e32 v[70:71], 0
	v_mov_b64_e32 v[72:73], 0
	v_mov_b64_e32 v[74:75], 0
	v_mov_b64_e32 v[76:77], 0
	v_mov_b64_e32 v[78:79], 0
	v_mov_b64_e32 v[80:81], 0
	v_mov_b64_e32 v[82:83], 0
	v_mov_b64_e32 v[84:85], 0
	v_mov_b64_e32 v[86:87], 0
	v_mov_b64_e32 v[88:89], 0
	v_mov_b64_e32 v[90:91], 0
	v_mov_b64_e32 v[92:93], 0
	v_mov_b64_e32 v[94:95], 0
	v_mov_b64_e32 v[96:97], 0
	v_mov_b64_e32 v[98:99], 0
	v_mov_b64_e32 v[100:101], 0
	v_mov_b64_e32 v[102:103], 0
	v_mov_b64_e32 v[104:105], 0
	v_mov_b64_e32 v[106:107], 0
	v_mov_b64_e32 v[108:109], 0
	v_mov_b64_e32 v[110:111], 0
	v_mov_b64_e32 v[112:113], 0
	v_mov_b64_e32 v[114:115], 0
	v_mov_b64_e32 v[116:117], 0
	v_mov_b64_e32 v[118:119], 0
	v_mov_b64_e32 v[120:121], 0
	v_mov_b64_e32 v[122:123], 0
	v_mov_b64_e32 v[124:125], 0
	v_mov_b64_e32 v[126:127], 0
	v_mov_b64_e32 v[128:129], 0
	v_mov_b64_e32 v[130:131], 0
	v_mov_b64_e32 v[132:133], 0
	v_mov_b64_e32 v[134:135], 0
	v_mov_b64_e32 v[136:137], 0
	v_mov_b64_e32 v[138:139], 0
	v_mov_b64_e32 v[140:141], 0
	v_mov_b64_e32 v[142:143], 0
	v_mov_b64_e32 v[144:145], 0
	v_mov_b64_e32 v[146:147], 0
	v_mov_b64_e32 v[148:149], 0
	v_mov_b64_e32 v[150:151], 0
	v_mov_b64_e32 v[152:153], 0
	v_mov_b64_e32 v[154:155], 0
	v_mov_b64_e32 v[156:157], 0
	v_mov_b64_e32 v[158:159], 0
	v_mov_b64_e32 v[160:161], 0
	s_addc_u32 s55, s31, 0
	v_lshl_add_u64 v[176:177], s[18:19], 0, v[174:175]
	v_lshl_add_u64 v[178:179], s[18:19], 0, v[172:173]
	s_mov_b32 s56, -2
	s_mov_b64 s[34:35], 0

.LBB0_754:
	s_ashr_i32 s19, s18, 31
	s_lshl_b64 s[0:1], s[18:19], 18
	v_cmp_lt_i64_e32 vcc, s[20:21], v[158:159]
	s_add_u32 s20, s5, s0
	s_addc_u32 s21, s6, s1
	s_and_b64 s[0:1], vcc, exec
	s_cselect_b32 s19, s21, s29
	s_cselect_b32 s49, s20, s28
	s_ashr_i32 s0, s18, 5
	s_ashr_i32 s1, s0, 31
	s_lshl_b64 s[0:1], s[0:1], 20
	s_add_u32 s22, s7, s0
	s_addc_u32 s23, s15, s1
	s_ashr_i32 s17, s16, 31
	s_lshl_b64 s[0:1], s[16:17], 18
	s_add_u32 s22, s22, s0
	s_addc_u32 s23, s23, s1
	s_and_b64 s[0:1], vcc, exec
	s_cselect_b32 s17, s23, s27
	s_cselect_b32 s50, s22, s26
	s_add_u32 s51, s26, 0x100
	s_addc_u32 s52, s27, 0
	s_add_u32 s26, s28, 0xc000
	v_mov_b64_e32 v[18:19], 0
	v_mov_b64_e32 v[20:21], 0
	v_mov_b64_e32 v[22:23], 0
	v_mov_b64_e32 v[24:25], 0
	v_mov_b64_e32 v[26:27], 0
	v_mov_b64_e32 v[28:29], 0
	v_mov_b64_e32 v[30:31], 0
	v_mov_b64_e32 v[32:33], 0
	v_mov_b64_e32 v[34:35], 0
	v_mov_b64_e32 v[36:37], 0
	v_mov_b64_e32 v[38:39], 0
	v_mov_b64_e32 v[40:41], 0
	v_mov_b64_e32 v[42:43], 0
	v_mov_b64_e32 v[44:45], 0
	v_mov_b64_e32 v[46:47], 0
	v_mov_b64_e32 v[48:49], 0
	v_mov_b64_e32 v[50:51], 0
	v_mov_b64_e32 v[52:53], 0
	v_mov_b64_e32 v[54:55], 0
	v_mov_b64_e32 v[56:57], 0
	v_mov_b64_e32 v[58:59], 0
	v_mov_b64_e32 v[60:61], 0
	v_mov_b64_e32 v[62:63], 0
	v_mov_b64_e32 v[64:65], 0
	v_mov_b64_e32 v[66:67], 0
	v_mov_b64_e32 v[68:69], 0
	v_mov_b64_e32 v[70:71], 0
	v_mov_b64_e32 v[72:73], 0
	v_mov_b64_e32 v[74:75], 0
	v_mov_b64_e32 v[76:77], 0
	v_mov_b64_e32 v[78:79], 0
	v_mov_b64_e32 v[80:81], 0
	v_mov_b64_e32 v[82:83], 0
	v_mov_b64_e32 v[84:85], 0
	v_mov_b64_e32 v[86:87], 0
	v_mov_b64_e32 v[88:89], 0
	v_mov_b64_e32 v[90:91], 0
	v_mov_b64_e32 v[92:93], 0
	v_mov_b64_e32 v[94:95], 0
	v_mov_b64_e32 v[96:97], 0
	v_mov_b64_e32 v[98:99], 0
	v_mov_b64_e32 v[100:101], 0
	v_mov_b64_e32 v[102:103], 0
	v_mov_b64_e32 v[104:105], 0
	v_mov_b64_e32 v[106:107], 0
	v_mov_b64_e32 v[108:109], 0
	v_mov_b64_e32 v[110:111], 0
	v_mov_b64_e32 v[112:113], 0
	v_mov_b64_e32 v[114:115], 0
	v_mov_b64_e32 v[116:117], 0
	v_mov_b64_e32 v[118:119], 0
	v_mov_b64_e32 v[120:121], 0
	v_mov_b64_e32 v[122:123], 0
	v_mov_b64_e32 v[124:125], 0
	v_mov_b64_e32 v[126:127], 0
	v_mov_b64_e32 v[128:129], 0
	v_mov_b64_e32 v[130:131], 0
	v_mov_b64_e32 v[132:133], 0
	v_mov_b64_e32 v[134:135], 0
	v_mov_b64_e32 v[136:137], 0
	v_mov_b64_e32 v[138:139], 0
	v_mov_b64_e32 v[140:141], 0
	v_mov_b64_e32 v[142:143], 0
	v_mov_b64_e32 v[144:145], 0
	s_addc_u32 s27, s29, 0
	s_mov_b32 s53, -2

.LBB0_894:
	s_ashr_i32 s23, s22, 31
	s_lshl_b64 s[0:1], s[22:23], 19
	v_cmp_lt_i64_e32 vcc, s[26:27], v[142:143]
	s_add_u32 s26, s5, s0
	s_addc_u32 s27, s6, s1
	s_and_b64 s[0:1], vcc, exec
	s_cselect_b32 s23, s27, s35
	s_cselect_b32 s51, s26, s34
	s_ashr_i32 s21, s20, 31
	s_lshl_b64 s[0:1], s[20:21], 19
	s_add_u32 s28, s7, s0
	s_addc_u32 s29, s10, s1
	s_and_b64 s[0:1], vcc, exec
	s_cselect_b32 s21, s29, s31
	s_cselect_b32 s52, s28, s30
	s_add_u32 s53, s30, 0x100
	s_addc_u32 s54, s31, 0
	s_add_u32 s30, s34, 0x40080
	v_mov_b64_e32 v[2:3], 0
	v_mov_b64_e32 v[4:5], 0
	v_mov_b64_e32 v[6:7], 0
	v_mov_b64_e32 v[8:9], 0
	v_mov_b64_e32 v[10:11], 0
	v_mov_b64_e32 v[12:13], 0
	v_mov_b64_e32 v[14:15], 0
	v_mov_b64_e32 v[16:17], 0
	v_mov_b64_e32 v[18:19], 0
	v_mov_b64_e32 v[20:21], 0
	v_mov_b64_e32 v[22:23], 0
	v_mov_b64_e32 v[24:25], 0
	v_mov_b64_e32 v[26:27], 0
	v_mov_b64_e32 v[28:29], 0
	v_mov_b64_e32 v[30:31], 0
	v_mov_b64_e32 v[32:33], 0
	v_mov_b64_e32 v[34:35], 0
	v_mov_b64_e32 v[36:37], 0
	v_mov_b64_e32 v[38:39], 0
	v_mov_b64_e32 v[40:41], 0
	v_mov_b64_e32 v[42:43], 0
	v_mov_b64_e32 v[44:45], 0
	v_mov_b64_e32 v[46:47], 0
	v_mov_b64_e32 v[48:49], 0
	v_mov_b64_e32 v[50:51], 0
	v_mov_b64_e32 v[52:53], 0
	v_mov_b64_e32 v[54:55], 0
	v_mov_b64_e32 v[56:57], 0
	v_mov_b64_e32 v[58:59], 0
	v_mov_b64_e32 v[60:61], 0
	v_mov_b64_e32 v[62:63], 0
	v_mov_b64_e32 v[64:65], 0
	v_mov_b64_e32 v[66:67], 0
	v_mov_b64_e32 v[68:69], 0
	v_mov_b64_e32 v[70:71], 0
	v_mov_b64_e32 v[72:73], 0
	v_mov_b64_e32 v[74:75], 0
	v_mov_b64_e32 v[76:77], 0
	v_mov_b64_e32 v[78:79], 0
	v_mov_b64_e32 v[80:81], 0
	v_mov_b64_e32 v[82:83], 0
	v_mov_b64_e32 v[84:85], 0
	v_mov_b64_e32 v[86:87], 0
	v_mov_b64_e32 v[88:89], 0
	v_mov_b64_e32 v[90:91], 0
	v_mov_b64_e32 v[92:93], 0
	v_mov_b64_e32 v[94:95], 0
	v_mov_b64_e32 v[96:97], 0
	v_mov_b64_e32 v[98:99], 0
	v_mov_b64_e32 v[100:101], 0
	v_mov_b64_e32 v[102:103], 0
	v_mov_b64_e32 v[104:105], 0
	v_mov_b64_e32 v[106:107], 0
	v_mov_b64_e32 v[108:109], 0
	v_mov_b64_e32 v[110:111], 0
	v_mov_b64_e32 v[112:113], 0
	v_mov_b64_e32 v[114:115], 0
	v_mov_b64_e32 v[116:117], 0
	v_mov_b64_e32 v[118:119], 0
	v_mov_b64_e32 v[120:121], 0
	v_mov_b64_e32 v[122:123], 0
	v_mov_b64_e32 v[124:125], 0
	v_mov_b64_e32 v[126:127], 0
	v_mov_b64_e32 v[128:129], 0
	s_addc_u32 s31, s35, 0
	s_mov_b32 s55, -2

.LBB0_1046:
	s_add_i32 s55, s55, 1
	s_mov_b64 s[0:1], s[26:27]
	s_lshr_b32 s26, s55, 2
	s_mul_i32 s26, s26, s74
	s_mov_b64 s[38:39], s[36:37]
	s_mov_b32 s37, s56
	s_add_i32 s56, s26, s2
	s_cmpk_lt_i32 s56, 0x100
	s_cselect_b64 s[40:41], -1, 0
	s_cmpk_gt_i32 s56, 0xff
	s_mov_b32 s36, s57
	s_cselect_b64 s[34:35], -1, 0
	s_and_b32 s57, s55, 3
	s_and_b64 s[26:27], s[40:41], exec
	s_cselect_b32 s26, s56, s37
	s_cselect_b32 s36, s57, s36
	s_ashr_i32 s27, s26, 31
	s_lshl_b64 s[26:27], s[26:27], 19
	s_add_u32 s26, s20, s26
	s_addc_u32 s27, s21, s27
	s_and_b64 s[42:43], s[40:41], exec
	s_cselect_b32 s60, s27, s1
	s_cselect_b32 s61, s26, s0
	s_ashr_i32 s37, s36, 31
	s_lshl_b64 s[36:37], s[36:37], 19
	s_add_u32 s36, s8, s36
	s_addc_u32 s37, s9, s37
	s_and_b64 s[40:41], s[40:41], exec
	s_cselect_b32 s62, s37, s39
	s_cselect_b32 s63, s36, s38
	s_add_u32 s64, s38, 0x100
	s_addc_u32 s65, s39, 0
	s_add_u32 s38, s0, 0x40080
	v_mov_b64_e32 v[2:3], 0
	v_mov_b64_e32 v[4:5], 0
	v_mov_b64_e32 v[6:7], 0
	v_mov_b64_e32 v[8:9], 0
	v_mov_b64_e32 v[10:11], 0
	v_mov_b64_e32 v[12:13], 0
	v_mov_b64_e32 v[14:15], 0
	v_mov_b64_e32 v[16:17], 0
	v_mov_b64_e32 v[18:19], 0
	v_mov_b64_e32 v[20:21], 0
	v_mov_b64_e32 v[22:23], 0
	v_mov_b64_e32 v[24:25], 0
	v_mov_b64_e32 v[26:27], 0
	v_mov_b64_e32 v[28:29], 0
	v_mov_b64_e32 v[30:31], 0
	v_mov_b64_e32 v[32:33], 0
	v_mov_b64_e32 v[34:35], 0
	v_mov_b64_e32 v[36:37], 0
	v_mov_b64_e32 v[38:39], 0
	v_mov_b64_e32 v[40:41], 0
	v_mov_b64_e32 v[42:43], 0
	v_mov_b64_e32 v[44:45], 0
	v_mov_b64_e32 v[46:47], 0
	v_mov_b64_e32 v[48:49], 0
	v_mov_b64_e32 v[50:51], 0
	v_mov_b64_e32 v[52:53], 0
	v_mov_b64_e32 v[54:55], 0
	v_mov_b64_e32 v[56:57], 0
	v_mov_b64_e32 v[58:59], 0
	v_mov_b64_e32 v[60:61], 0
	v_mov_b64_e32 v[62:63], 0
	v_mov_b64_e32 v[64:65], 0
	v_mov_b64_e32 v[66:67], 0
	v_mov_b64_e32 v[68:69], 0
	v_mov_b64_e32 v[70:71], 0
	v_mov_b64_e32 v[72:73], 0
	v_mov_b64_e32 v[74:75], 0
	v_mov_b64_e32 v[76:77], 0
	v_mov_b64_e32 v[78:79], 0
	v_mov_b64_e32 v[80:81], 0
	v_mov_b64_e32 v[82:83], 0
	v_mov_b64_e32 v[84:85], 0
	v_mov_b64_e32 v[86:87], 0
	v_mov_b64_e32 v[88:89], 0
	v_mov_b64_e32 v[90:91], 0
	v_mov_b64_e32 v[92:93], 0
	v_mov_b64_e32 v[94:95], 0
	v_mov_b64_e32 v[96:97], 0
	v_mov_b64_e32 v[98:99], 0
	v_mov_b64_e32 v[100:101], 0
	v_mov_b64_e32 v[102:103], 0
	v_mov_b64_e32 v[104:105], 0
	v_mov_b64_e32 v[106:107], 0
	v_mov_b64_e32 v[108:109], 0
	v_mov_b64_e32 v[110:111], 0
	v_mov_b64_e32 v[112:113], 0
	v_mov_b64_e32 v[114:115], 0
	v_mov_b64_e32 v[116:117], 0
	v_mov_b64_e32 v[118:119], 0
	v_mov_b64_e32 v[120:121], 0
	v_mov_b64_e32 v[122:123], 0
	v_mov_b64_e32 v[124:125], 0
	v_mov_b64_e32 v[126:127], 0
	v_mov_b64_e32 v[128:129], 0
	s_addc_u32 s39, s1, 0
	s_mov_b32 s69, -2
	s_waitcnt vmcnt(0)

.LBB0_1301:
	s_ashr_i32 s0, s54, 5
	s_ashr_i32 s1, s0, 31
	s_lshl_b64 s[0:1], s[0:1], 21
	s_add_u32 s14, s4, s0
	s_addc_u32 s15, s5, s1
	s_ashr_i32 s27, s26, 31
	s_lshl_b64 s[0:1], s[26:27], 18
	s_add_u32 s14, s14, s0
	s_addc_u32 s15, s15, s1
	s_and_b64 s[0:1], s[12:13], exec
	s_cselect_b32 s27, s15, s35
	s_cselect_b32 s29, s14, s34
	v_mov_b32_e32 v173, v163
	v_mov_b32_e32 v175, v163
	s_add_u32 s31, s34, 0x100
	v_mov_b64_e32 v[34:35], 0
	v_mov_b64_e32 v[36:37], 0
	v_mov_b64_e32 v[38:39], 0
	v_mov_b64_e32 v[40:41], 0
	v_mov_b64_e32 v[42:43], 0
	v_mov_b64_e32 v[44:45], 0
	v_mov_b64_e32 v[46:47], 0
	v_mov_b64_e32 v[48:49], 0
	v_mov_b64_e32 v[50:51], 0
	v_mov_b64_e32 v[52:53], 0
	v_mov_b64_e32 v[54:55], 0
	v_mov_b64_e32 v[56:57], 0
	v_mov_b64_e32 v[58:59], 0
	v_mov_b64_e32 v[60:61], 0
	v_mov_b64_e32 v[62:63], 0
	v_mov_b64_e32 v[64:65], 0
	v_mov_b64_e32 v[66:67], 0
	v_mov_b64_e32 v[68:69], 0
	v_mov_b64_e32 v[70:71], 0
	v_mov_b64_e32 v[72:73], 0
	v_mov_b64_e32 v[74:75], 0
	v_mov_b64_e32 v[76:77], 0
	v_mov_b64_e32 v[78:79], 0
	v_mov_b64_e32 v[80:81], 0
	v_mov_b64_e32 v[82:83], 0
	v_mov_b64_e32 v[84:85], 0
	v_mov_b64_e32 v[86:87], 0
	v_mov_b64_e32 v[88:89], 0
	v_mov_b64_e32 v[90:91], 0
	v_mov_b64_e32 v[92:93], 0
	v_mov_b64_e32 v[94:95], 0
	v_mov_b64_e32 v[96:97], 0
	v_mov_b64_e32 v[98:99], 0
	v_mov_b64_e32 v[100:101], 0
	v_mov_b64_e32 v[102:103], 0
	v_mov_b64_e32 v[104:105], 0
	v_mov_b64_e32 v[106:107], 0
	v_mov_b64_e32 v[108:109], 0
	v_mov_b64_e32 v[110:111], 0
	v_mov_b64_e32 v[112:113], 0
	v_mov_b64_e32 v[114:115], 0
	v_mov_b64_e32 v[116:117], 0
	v_mov_b64_e32 v[118:119], 0
	v_mov_b64_e32 v[120:121], 0
	v_mov_b64_e32 v[122:123], 0
	v_mov_b64_e32 v[124:125], 0
	v_mov_b64_e32 v[126:127], 0
	v_mov_b64_e32 v[128:129], 0
	v_mov_b64_e32 v[130:131], 0
	v_mov_b64_e32 v[132:133], 0
	v_mov_b64_e32 v[134:135], 0
	v_mov_b64_e32 v[136:137], 0
	v_mov_b64_e32 v[138:139], 0
	v_mov_b64_e32 v[140:141], 0
	v_mov_b64_e32 v[142:143], 0
	v_mov_b64_e32 v[144:145], 0
	v_mov_b64_e32 v[146:147], 0
	v_mov_b64_e32 v[148:149], 0
	v_mov_b64_e32 v[150:151], 0
	v_mov_b64_e32 v[152:153], 0
	v_mov_b64_e32 v[154:155], 0
	v_mov_b64_e32 v[156:157], 0
	v_mov_b64_e32 v[158:159], 0
	v_mov_b64_e32 v[160:161], 0
	s_addc_u32 s55, s35, 0
	v_lshl_add_u64 v[176:177], s[20:21], 0, v[174:175]
	v_lshl_add_u64 v[178:179], s[20:21], 0, v[172:173]
	s_mov_b32 s56, -2
	s_mov_b64 s[36:37], 0

.LBB0_1368:
	s_ashr_i32 s21, s20, 31
	s_lshl_b64 s[0:1], s[20:21], 18
	v_cmp_lt_i64_e32 vcc, s[22:23], v[158:159]
	s_add_u32 s22, s5, s0
	s_addc_u32 s23, s6, s1
	s_and_b64 s[0:1], vcc, exec
	s_cselect_b32 s21, s23, s31
	s_cselect_b32 s49, s22, s30
	s_ashr_i32 s0, s20, 5
	s_ashr_i32 s1, s0, 31
	s_lshl_b64 s[0:1], s[0:1], 20
	s_add_u32 s24, s7, s0
	s_addc_u32 s25, s10, s1
	s_ashr_i32 s19, s18, 31
	s_lshl_b64 s[0:1], s[18:19], 18
	s_add_u32 s24, s24, s0
	s_addc_u32 s25, s25, s1
	s_and_b64 s[0:1], vcc, exec
	s_cselect_b32 s19, s25, s29
	s_cselect_b32 s50, s24, s28
	s_add_u32 s51, s28, 0x100
	s_addc_u32 s52, s29, 0
	s_add_u32 s28, s30, 0xc000
	v_mov_b64_e32 v[18:19], 0
	v_mov_b64_e32 v[20:21], 0
	v_mov_b64_e32 v[22:23], 0
	v_mov_b64_e32 v[24:25], 0
	v_mov_b64_e32 v[26:27], 0
	v_mov_b64_e32 v[28:29], 0
	v_mov_b64_e32 v[30:31], 0
	v_mov_b64_e32 v[32:33], 0
	v_mov_b64_e32 v[34:35], 0
	v_mov_b64_e32 v[36:37], 0
	v_mov_b64_e32 v[38:39], 0
	v_mov_b64_e32 v[40:41], 0
	v_mov_b64_e32 v[42:43], 0
	v_mov_b64_e32 v[44:45], 0
	v_mov_b64_e32 v[46:47], 0
	v_mov_b64_e32 v[48:49], 0
	v_mov_b64_e32 v[50:51], 0
	v_mov_b64_e32 v[52:53], 0
	v_mov_b64_e32 v[54:55], 0
	v_mov_b64_e32 v[56:57], 0
	v_mov_b64_e32 v[58:59], 0
	v_mov_b64_e32 v[60:61], 0
	v_mov_b64_e32 v[62:63], 0
	v_mov_b64_e32 v[64:65], 0
	v_mov_b64_e32 v[66:67], 0
	v_mov_b64_e32 v[68:69], 0
	v_mov_b64_e32 v[70:71], 0
	v_mov_b64_e32 v[72:73], 0
	v_mov_b64_e32 v[74:75], 0
	v_mov_b64_e32 v[76:77], 0
	v_mov_b64_e32 v[78:79], 0
	v_mov_b64_e32 v[80:81], 0
	v_mov_b64_e32 v[82:83], 0
	v_mov_b64_e32 v[84:85], 0
	v_mov_b64_e32 v[86:87], 0
	v_mov_b64_e32 v[88:89], 0
	v_mov_b64_e32 v[90:91], 0
	v_mov_b64_e32 v[92:93], 0
	v_mov_b64_e32 v[94:95], 0
	v_mov_b64_e32 v[96:97], 0
	v_mov_b64_e32 v[98:99], 0
	v_mov_b64_e32 v[100:101], 0
	v_mov_b64_e32 v[102:103], 0
	v_mov_b64_e32 v[104:105], 0
	v_mov_b64_e32 v[106:107], 0
	v_mov_b64_e32 v[108:109], 0
	v_mov_b64_e32 v[110:111], 0
	v_mov_b64_e32 v[112:113], 0
	v_mov_b64_e32 v[114:115], 0
	v_mov_b64_e32 v[116:117], 0
	v_mov_b64_e32 v[118:119], 0
	v_mov_b64_e32 v[120:121], 0
	v_mov_b64_e32 v[122:123], 0
	v_mov_b64_e32 v[124:125], 0
	v_mov_b64_e32 v[126:127], 0
	v_mov_b64_e32 v[128:129], 0
	v_mov_b64_e32 v[130:131], 0
	v_mov_b64_e32 v[132:133], 0
	v_mov_b64_e32 v[134:135], 0
	v_mov_b64_e32 v[136:137], 0
	v_mov_b64_e32 v[138:139], 0
	v_mov_b64_e32 v[140:141], 0
	v_mov_b64_e32 v[142:143], 0
	v_mov_b64_e32 v[144:145], 0
	s_addc_u32 s29, s31, 0
	s_mov_b32 s53, -2

.LBB0_1512:
	s_ashr_i32 s21, s20, 31
	s_lshl_b64 s[0:1], s[20:21], 19
	v_cmp_lt_i64_e32 vcc, s[22:23], v[142:143]
	s_add_u32 s22, s5, s0
	s_addc_u32 s23, s6, s1
	s_and_b64 s[0:1], vcc, exec
	s_cselect_b32 s21, s23, s29
	s_cselect_b32 s45, s22, s28
	s_ashr_i32 s19, s18, 31
	s_lshl_b64 s[0:1], s[18:19], 19
	s_add_u32 s24, s7, s0
	s_addc_u32 s25, s8, s1
	s_and_b64 s[0:1], vcc, exec
	s_cselect_b32 s19, s25, s27
	s_cselect_b32 s46, s24, s26
	s_add_u32 s47, s26, 0x100
	s_addc_u32 s48, s27, 0
	s_add_u32 s26, s28, 0x40080
	v_mov_b64_e32 v[2:3], 0
	v_mov_b64_e32 v[4:5], 0
	v_mov_b64_e32 v[6:7], 0
	v_mov_b64_e32 v[8:9], 0
	v_mov_b64_e32 v[10:11], 0
	v_mov_b64_e32 v[12:13], 0
	v_mov_b64_e32 v[14:15], 0
	v_mov_b64_e32 v[16:17], 0
	v_mov_b64_e32 v[18:19], 0
	v_mov_b64_e32 v[20:21], 0
	v_mov_b64_e32 v[22:23], 0
	v_mov_b64_e32 v[24:25], 0
	v_mov_b64_e32 v[26:27], 0
	v_mov_b64_e32 v[28:29], 0
	v_mov_b64_e32 v[30:31], 0
	v_mov_b64_e32 v[32:33], 0
	v_mov_b64_e32 v[34:35], 0
	v_mov_b64_e32 v[36:37], 0
	v_mov_b64_e32 v[38:39], 0
	v_mov_b64_e32 v[40:41], 0
	v_mov_b64_e32 v[42:43], 0
	v_mov_b64_e32 v[44:45], 0
	v_mov_b64_e32 v[46:47], 0
	v_mov_b64_e32 v[48:49], 0
	v_mov_b64_e32 v[50:51], 0
	v_mov_b64_e32 v[52:53], 0
	v_mov_b64_e32 v[54:55], 0
	v_mov_b64_e32 v[56:57], 0
	v_mov_b64_e32 v[58:59], 0
	v_mov_b64_e32 v[60:61], 0
	v_mov_b64_e32 v[62:63], 0
	v_mov_b64_e32 v[64:65], 0
	v_mov_b64_e32 v[66:67], 0
	v_mov_b64_e32 v[68:69], 0
	v_mov_b64_e32 v[70:71], 0
	v_mov_b64_e32 v[72:73], 0
	v_mov_b64_e32 v[74:75], 0
	v_mov_b64_e32 v[76:77], 0
	v_mov_b64_e32 v[78:79], 0
	v_mov_b64_e32 v[80:81], 0
	v_mov_b64_e32 v[82:83], 0
	v_mov_b64_e32 v[84:85], 0
	v_mov_b64_e32 v[86:87], 0
	v_mov_b64_e32 v[88:89], 0
	v_mov_b64_e32 v[90:91], 0
	v_mov_b64_e32 v[92:93], 0
	v_mov_b64_e32 v[94:95], 0
	v_mov_b64_e32 v[96:97], 0
	v_mov_b64_e32 v[98:99], 0
	v_mov_b64_e32 v[100:101], 0
	v_mov_b64_e32 v[102:103], 0
	v_mov_b64_e32 v[104:105], 0
	v_mov_b64_e32 v[106:107], 0
	v_mov_b64_e32 v[108:109], 0
	v_mov_b64_e32 v[110:111], 0
	v_mov_b64_e32 v[112:113], 0
	v_mov_b64_e32 v[114:115], 0
	v_mov_b64_e32 v[116:117], 0
	v_mov_b64_e32 v[118:119], 0
	v_mov_b64_e32 v[120:121], 0
	v_mov_b64_e32 v[122:123], 0
	v_mov_b64_e32 v[124:125], 0
	v_mov_b64_e32 v[126:127], 0
	v_mov_b64_e32 v[128:129], 0
	s_addc_u32 s27, s29, 0
	s_mov_b32 s49, -2

.LBB0_1644:
	s_ashr_i32 s43, s42, 31
	s_lshl_b64 s[0:1], s[42:43], 19
	s_add_u32 s0, s24, s0
	s_addc_u32 s1, s25, s1
	s_lshl_b32 s41, s40, 8
	s_and_b32 s41, s41, 0x600
	v_cmp_lt_i64_e32 vcc, s[44:45], v[162:163]
	s_add_u32 s44, s0, s41
	s_addc_u32 s45, s1, 0
	s_and_b64 s[0:1], vcc, exec
	s_cselect_b32 s43, s45, s49
	s_cselect_b32 s83, s44, s48
	s_ashr_i32 s41, s40, 31
	s_lshl_b64 s[0:1], s[40:41], 17
	s_add_u32 s46, s31, s0
	s_addc_u32 s47, s35, s1
	s_and_b64 s[0:1], vcc, exec
	v_mov_b64_e32 v[2:3], 0
	v_mov_b64_e32 v[4:5], 0
	v_mov_b64_e32 v[6:7], 0
	v_mov_b64_e32 v[8:9], 0
	v_mov_b64_e32 v[10:11], 0
	v_mov_b64_e32 v[12:13], 0
	v_mov_b64_e32 v[14:15], 0
	v_mov_b64_e32 v[16:17], 0
	v_mov_b64_e32 v[18:19], 0
	v_mov_b64_e32 v[20:21], 0
	v_mov_b64_e32 v[22:23], 0
	v_mov_b64_e32 v[24:25], 0
	v_mov_b64_e32 v[34:35], 0
	v_mov_b64_e32 v[36:37], 0
	v_mov_b64_e32 v[38:39], 0
	v_mov_b64_e32 v[40:41], 0
	v_mov_b64_e32 v[50:51], 0
	v_mov_b64_e32 v[52:53], 0
	v_mov_b64_e32 v[54:55], 0
	v_mov_b64_e32 v[56:57], 0
	v_mov_b64_e32 v[58:59], 0
	v_mov_b64_e32 v[60:61], 0
	v_mov_b64_e32 v[62:63], 0
	v_mov_b64_e32 v[64:65], 0
	v_mov_b64_e32 v[66:67], 0
	v_mov_b64_e32 v[68:69], 0
	v_mov_b64_e32 v[70:71], 0
	v_mov_b64_e32 v[72:73], 0
	v_mov_b64_e32 v[74:75], 0
	v_mov_b64_e32 v[76:77], 0
	v_mov_b64_e32 v[78:79], 0
	v_mov_b64_e32 v[80:81], 0
	v_mov_b64_e32 v[82:83], 0
	v_mov_b64_e32 v[84:85], 0
	v_mov_b64_e32 v[86:87], 0
	v_mov_b64_e32 v[88:89], 0
	v_mov_b64_e32 v[90:91], 0
	v_mov_b64_e32 v[92:93], 0
	v_mov_b64_e32 v[94:95], 0
	v_mov_b64_e32 v[96:97], 0
	v_mov_b64_e32 v[98:99], 0
	v_mov_b64_e32 v[100:101], 0
	v_mov_b64_e32 v[102:103], 0
	v_mov_b64_e32 v[104:105], 0
	v_mov_b64_e32 v[106:107], 0
	v_mov_b64_e32 v[108:109], 0
	v_mov_b64_e32 v[110:111], 0
	v_mov_b64_e32 v[112:113], 0
	v_mov_b64_e32 v[114:115], 0
	v_mov_b64_e32 v[116:117], 0
	v_mov_b64_e32 v[118:119], 0
	v_mov_b64_e32 v[120:121], 0
	v_mov_b64_e32 v[122:123], 0
	v_mov_b64_e32 v[124:125], 0
	v_mov_b64_e32 v[126:127], 0
	v_mov_b64_e32 v[128:129], 0
	v_mov_b64_e32 v[130:131], 0
	v_mov_b64_e32 v[132:133], 0
	v_mov_b64_e32 v[134:135], 0
	v_mov_b64_e32 v[136:137], 0
	v_mov_b64_e32 v[138:139], 0
	v_mov_b64_e32 v[140:141], 0
	v_mov_b64_e32 v[142:143], 0
	v_mov_b64_e32 v[144:145], 0
	s_mov_b32 s23, s94
	s_cselect_b32 s41, s47, s15
	s_cselect_b32 s94, s46, s14
	s_mov_b32 s56, 0
	s_mov_b64 s[50:51], -1
	s_mov_b64 s[54:55], 0

.LBB0_1785:
	s_add_i32 s55, s55, 1
	s_mov_b64 s[0:1], s[26:27]
	s_lshr_b32 s26, s55, 2
	s_mul_i32 s26, s26, s74
	s_mov_b64 s[38:39], s[36:37]
	s_mov_b32 s37, s56
	s_add_i32 s56, s26, s2
	s_cmpk_lt_i32 s56, 0x100
	s_cselect_b64 s[40:41], -1, 0
	s_cmpk_gt_i32 s56, 0xff
	s_mov_b32 s36, s57
	s_cselect_b64 s[34:35], -1, 0
	s_and_b32 s57, s55, 3
	s_and_b64 s[26:27], s[40:41], exec
	s_cselect_b32 s26, s56, s37
	s_cselect_b32 s36, s57, s36
	s_ashr_i32 s27, s26, 31
	s_lshl_b64 s[26:27], s[26:27], 19
	s_add_u32 s26, s5, s26
	s_addc_u32 s27, s6, s27
	s_and_b64 s[42:43], s[40:41], exec
	s_cselect_b32 s60, s27, s1
	s_cselect_b32 s61, s26, s0
	s_ashr_i32 s37, s36, 31
	s_lshl_b64 s[36:37], s[36:37], 19
	s_add_u32 s36, s24, s36
	s_addc_u32 s37, s25, s37
	s_and_b64 s[40:41], s[40:41], exec
	s_cselect_b32 s62, s37, s39
	s_cselect_b32 s63, s36, s38
	s_add_u32 s64, s38, 0x100
	s_addc_u32 s65, s39, 0
	s_add_u32 s38, s0, 0x40080
	v_mov_b64_e32 v[2:3], 0
	v_mov_b64_e32 v[4:5], 0
	v_mov_b64_e32 v[6:7], 0
	v_mov_b64_e32 v[8:9], 0
	v_mov_b64_e32 v[10:11], 0
	v_mov_b64_e32 v[12:13], 0
	v_mov_b64_e32 v[14:15], 0
	v_mov_b64_e32 v[16:17], 0
	v_mov_b64_e32 v[18:19], 0
	v_mov_b64_e32 v[20:21], 0
	v_mov_b64_e32 v[22:23], 0
	v_mov_b64_e32 v[24:25], 0
	v_mov_b64_e32 v[26:27], 0
	v_mov_b64_e32 v[28:29], 0
	v_mov_b64_e32 v[30:31], 0
	v_mov_b64_e32 v[32:33], 0
	v_mov_b64_e32 v[34:35], 0
	v_mov_b64_e32 v[36:37], 0
	v_mov_b64_e32 v[38:39], 0
	v_mov_b64_e32 v[40:41], 0
	v_mov_b64_e32 v[42:43], 0
	v_mov_b64_e32 v[44:45], 0
	v_mov_b64_e32 v[46:47], 0
	v_mov_b64_e32 v[48:49], 0
	v_mov_b64_e32 v[50:51], 0
	v_mov_b64_e32 v[52:53], 0
	v_mov_b64_e32 v[54:55], 0
	v_mov_b64_e32 v[56:57], 0
	v_mov_b64_e32 v[58:59], 0
	v_mov_b64_e32 v[60:61], 0
	v_mov_b64_e32 v[62:63], 0
	v_mov_b64_e32 v[64:65], 0
	v_mov_b64_e32 v[66:67], 0
	v_mov_b64_e32 v[68:69], 0
	v_mov_b64_e32 v[70:71], 0
	v_mov_b64_e32 v[72:73], 0
	v_mov_b64_e32 v[74:75], 0
	v_mov_b64_e32 v[76:77], 0
	v_mov_b64_e32 v[78:79], 0
	v_mov_b64_e32 v[80:81], 0
	v_mov_b64_e32 v[82:83], 0
	v_mov_b64_e32 v[84:85], 0
	v_mov_b64_e32 v[86:87], 0
	v_mov_b64_e32 v[88:89], 0
	v_mov_b64_e32 v[90:91], 0
	v_mov_b64_e32 v[92:93], 0
	v_mov_b64_e32 v[94:95], 0
	v_mov_b64_e32 v[96:97], 0
	v_mov_b64_e32 v[98:99], 0
	v_mov_b64_e32 v[100:101], 0
	v_mov_b64_e32 v[102:103], 0
	v_mov_b64_e32 v[104:105], 0
	v_mov_b64_e32 v[106:107], 0
	v_mov_b64_e32 v[108:109], 0
	v_mov_b64_e32 v[110:111], 0
	v_mov_b64_e32 v[112:113], 0
	v_mov_b64_e32 v[114:115], 0
	v_mov_b64_e32 v[116:117], 0
	v_mov_b64_e32 v[118:119], 0
	v_mov_b64_e32 v[120:121], 0
	v_mov_b64_e32 v[122:123], 0
	v_mov_b64_e32 v[124:125], 0
	v_mov_b64_e32 v[126:127], 0
	v_mov_b64_e32 v[128:129], 0
	s_addc_u32 s39, s1, 0
	s_mov_b32 s66, -2

.LBB0_2040:
	s_ashr_i32 s0, s54, 5
	s_ashr_i32 s1, s0, 31
	s_lshl_b64 s[0:1], s[0:1], 21
	s_add_u32 s16, s4, s0
	s_addc_u32 s17, s5, s1
	s_ashr_i32 s29, s28, 31
	s_lshl_b64 s[0:1], s[28:29], 18
	s_add_u32 s16, s16, s0
	s_addc_u32 s17, s17, s1
	s_and_b64 s[0:1], s[14:15], exec
	s_cselect_b32 s29, s17, s37
	s_cselect_b32 s31, s16, s36
	v_mov_b32_e32 v173, v163
	v_mov_b32_e32 v175, v163
	s_add_u32 s35, s36, 0x100
	v_mov_b64_e32 v[34:35], 0
	v_mov_b64_e32 v[36:37], 0
	v_mov_b64_e32 v[38:39], 0
	v_mov_b64_e32 v[40:41], 0
	v_mov_b64_e32 v[42:43], 0
	v_mov_b64_e32 v[44:45], 0
	v_mov_b64_e32 v[46:47], 0
	v_mov_b64_e32 v[48:49], 0
	v_mov_b64_e32 v[50:51], 0
	v_mov_b64_e32 v[52:53], 0
	v_mov_b64_e32 v[54:55], 0
	v_mov_b64_e32 v[56:57], 0
	v_mov_b64_e32 v[58:59], 0
	v_mov_b64_e32 v[60:61], 0
	v_mov_b64_e32 v[62:63], 0
	v_mov_b64_e32 v[64:65], 0
	v_mov_b64_e32 v[66:67], 0
	v_mov_b64_e32 v[68:69], 0
	v_mov_b64_e32 v[70:71], 0
	v_mov_b64_e32 v[72:73], 0
	v_mov_b64_e32 v[74:75], 0
	v_mov_b64_e32 v[76:77], 0
	v_mov_b64_e32 v[78:79], 0
	v_mov_b64_e32 v[80:81], 0
	v_mov_b64_e32 v[82:83], 0
	v_mov_b64_e32 v[84:85], 0
	v_mov_b64_e32 v[86:87], 0
	v_mov_b64_e32 v[88:89], 0
	v_mov_b64_e32 v[90:91], 0
	v_mov_b64_e32 v[92:93], 0
	v_mov_b64_e32 v[94:95], 0
	v_mov_b64_e32 v[96:97], 0
	v_mov_b64_e32 v[98:99], 0
	v_mov_b64_e32 v[100:101], 0
	v_mov_b64_e32 v[102:103], 0
	v_mov_b64_e32 v[104:105], 0
	v_mov_b64_e32 v[106:107], 0
	v_mov_b64_e32 v[108:109], 0
	v_mov_b64_e32 v[110:111], 0
	v_mov_b64_e32 v[112:113], 0
	v_mov_b64_e32 v[114:115], 0
	v_mov_b64_e32 v[116:117], 0
	v_mov_b64_e32 v[118:119], 0
	v_mov_b64_e32 v[120:121], 0
	v_mov_b64_e32 v[122:123], 0
	v_mov_b64_e32 v[124:125], 0
	v_mov_b64_e32 v[126:127], 0
	v_mov_b64_e32 v[128:129], 0
	v_mov_b64_e32 v[130:131], 0
	v_mov_b64_e32 v[132:133], 0
	v_mov_b64_e32 v[134:135], 0
	v_mov_b64_e32 v[136:137], 0
	v_mov_b64_e32 v[138:139], 0
	v_mov_b64_e32 v[140:141], 0
	v_mov_b64_e32 v[142:143], 0
	v_mov_b64_e32 v[144:145], 0
	v_mov_b64_e32 v[146:147], 0
	v_mov_b64_e32 v[148:149], 0
	v_mov_b64_e32 v[150:151], 0
	v_mov_b64_e32 v[152:153], 0
	v_mov_b64_e32 v[154:155], 0
	v_mov_b64_e32 v[156:157], 0
	v_mov_b64_e32 v[158:159], 0
	v_mov_b64_e32 v[160:161], 0
	s_addc_u32 s55, s37, 0
	v_lshl_add_u64 v[176:177], s[22:23], 0, v[174:175]
	v_lshl_add_u64 v[178:179], s[22:23], 0, v[172:173]
	s_mov_b32 s56, -2
	s_mov_b64 s[38:39], 0

.LBB0_2107:
	s_ashr_i32 s23, s22, 31
	s_lshl_b64 s[0:1], s[22:23], 18
	v_cmp_lt_i64_e32 vcc, s[24:25], v[158:159]
	s_add_u32 s24, s5, s0
	s_addc_u32 s25, s6, s1
	s_and_b64 s[0:1], vcc, exec
	s_cselect_b32 s23, s25, s35
	s_cselect_b32 s49, s24, s34
	s_ashr_i32 s0, s22, 5
	s_ashr_i32 s1, s0, 31
	s_lshl_b64 s[0:1], s[0:1], 20
	s_add_u32 s26, s7, s0
	s_addc_u32 s27, s8, s1
	s_ashr_i32 s21, s20, 31
	s_lshl_b64 s[0:1], s[20:21], 18
	s_add_u32 s26, s26, s0
	s_addc_u32 s27, s27, s1
	s_and_b64 s[0:1], vcc, exec
	s_cselect_b32 s21, s27, s31
	s_cselect_b32 s50, s26, s30
	s_add_u32 s51, s30, 0x100
	s_addc_u32 s52, s31, 0
	s_add_u32 s30, s34, 0xc000
	v_mov_b64_e32 v[18:19], 0
	v_mov_b64_e32 v[20:21], 0
	v_mov_b64_e32 v[22:23], 0
	v_mov_b64_e32 v[24:25], 0
	v_mov_b64_e32 v[26:27], 0
	v_mov_b64_e32 v[28:29], 0
	v_mov_b64_e32 v[30:31], 0
	v_mov_b64_e32 v[32:33], 0
	v_mov_b64_e32 v[34:35], 0
	v_mov_b64_e32 v[36:37], 0
	v_mov_b64_e32 v[38:39], 0
	v_mov_b64_e32 v[40:41], 0
	v_mov_b64_e32 v[42:43], 0
	v_mov_b64_e32 v[44:45], 0
	v_mov_b64_e32 v[46:47], 0
	v_mov_b64_e32 v[48:49], 0
	v_mov_b64_e32 v[50:51], 0
	v_mov_b64_e32 v[52:53], 0
	v_mov_b64_e32 v[54:55], 0
	v_mov_b64_e32 v[56:57], 0
	v_mov_b64_e32 v[58:59], 0
	v_mov_b64_e32 v[60:61], 0
	v_mov_b64_e32 v[62:63], 0
	v_mov_b64_e32 v[64:65], 0
	v_mov_b64_e32 v[66:67], 0
	v_mov_b64_e32 v[68:69], 0
	v_mov_b64_e32 v[70:71], 0
	v_mov_b64_e32 v[72:73], 0
	v_mov_b64_e32 v[74:75], 0
	v_mov_b64_e32 v[76:77], 0
	v_mov_b64_e32 v[78:79], 0
	v_mov_b64_e32 v[80:81], 0
	v_mov_b64_e32 v[82:83], 0
	v_mov_b64_e32 v[84:85], 0
	v_mov_b64_e32 v[86:87], 0
	v_mov_b64_e32 v[88:89], 0
	v_mov_b64_e32 v[90:91], 0
	v_mov_b64_e32 v[92:93], 0
	v_mov_b64_e32 v[94:95], 0
	v_mov_b64_e32 v[96:97], 0
	v_mov_b64_e32 v[98:99], 0
	v_mov_b64_e32 v[100:101], 0
	v_mov_b64_e32 v[102:103], 0
	v_mov_b64_e32 v[104:105], 0
	v_mov_b64_e32 v[106:107], 0
	v_mov_b64_e32 v[108:109], 0
	v_mov_b64_e32 v[110:111], 0
	v_mov_b64_e32 v[112:113], 0
	v_mov_b64_e32 v[114:115], 0
	v_mov_b64_e32 v[116:117], 0
	v_mov_b64_e32 v[118:119], 0
	v_mov_b64_e32 v[120:121], 0
	v_mov_b64_e32 v[122:123], 0
	v_mov_b64_e32 v[124:125], 0
	v_mov_b64_e32 v[126:127], 0
	v_mov_b64_e32 v[128:129], 0
	v_mov_b64_e32 v[130:131], 0
	v_mov_b64_e32 v[132:133], 0
	v_mov_b64_e32 v[134:135], 0
	v_mov_b64_e32 v[136:137], 0
	v_mov_b64_e32 v[138:139], 0
	v_mov_b64_e32 v[140:141], 0
	v_mov_b64_e32 v[142:143], 0
	v_mov_b64_e32 v[144:145], 0
	s_addc_u32 s31, s35, 0
	s_mov_b32 s53, -2

.LBB0_2244:
	s_add_i32 s50, s50, 1
	s_mov_b64 s[0:1], s[16:17]
	s_mul_hi_u32 s16, s50, 0xaaaaaaab
	s_lshr_b32 s16, s16, 1
	s_mul_i32 s17, s16, s74
	s_mov_b64 s[30:31], s[28:29]
	s_mov_b32 s29, s51
	s_add_i32 s51, s17, s2
	s_cmpk_lt_i32 s51, 0x100
	s_cselect_b64 s[34:35], -1, 0
	s_cmpk_gt_i32 s51, 0xff
	s_mul_i32 s16, s16, 3
	s_mov_b32 s28, s52
	s_cselect_b64 s[26:27], -1, 0
	s_sub_i32 s52, s50, s16
	s_and_b64 s[16:17], s[34:35], exec
	s_cselect_b32 s16, s51, s29
	s_cselect_b32 s28, s52, s28
	s_ashr_i32 s17, s16, 31
	s_lshl_b64 s[16:17], s[16:17], 19
	s_add_u32 s16, s6, s16
	s_addc_u32 s17, s7, s17
	s_and_b64 s[36:37], s[34:35], exec
	s_cselect_b32 s55, s17, s1
	s_cselect_b32 s56, s16, s0
	s_ashr_i32 s29, s28, 31
	s_lshl_b64 s[28:29], s[28:29], 19
	s_add_u32 s28, s10, s28
	s_addc_u32 s29, s11, s29
	s_and_b64 s[34:35], s[34:35], exec
	s_cselect_b32 s57, s29, s31
	s_cselect_b32 s58, s28, s30
	s_add_u32 s59, s30, 0x100
	s_addc_u32 s60, s31, 0
	s_add_u32 s30, s0, 0x40080
	v_mov_b64_e32 v[2:3], 0
	v_mov_b64_e32 v[4:5], 0
	v_mov_b64_e32 v[6:7], 0
	v_mov_b64_e32 v[8:9], 0
	v_mov_b64_e32 v[10:11], 0
	v_mov_b64_e32 v[12:13], 0
	v_mov_b64_e32 v[14:15], 0
	v_mov_b64_e32 v[16:17], 0
	v_mov_b64_e32 v[18:19], 0
	v_mov_b64_e32 v[20:21], 0
	v_mov_b64_e32 v[22:23], 0
	v_mov_b64_e32 v[24:25], 0
	v_mov_b64_e32 v[26:27], 0
	v_mov_b64_e32 v[28:29], 0
	v_mov_b64_e32 v[30:31], 0
	v_mov_b64_e32 v[32:33], 0
	v_mov_b64_e32 v[34:35], 0
	v_mov_b64_e32 v[36:37], 0
	v_mov_b64_e32 v[38:39], 0
	v_mov_b64_e32 v[40:41], 0
	v_mov_b64_e32 v[42:43], 0
	v_mov_b64_e32 v[44:45], 0
	v_mov_b64_e32 v[46:47], 0
	v_mov_b64_e32 v[48:49], 0
	v_mov_b64_e32 v[50:51], 0
	v_mov_b64_e32 v[52:53], 0
	v_mov_b64_e32 v[54:55], 0
	v_mov_b64_e32 v[56:57], 0
	v_mov_b64_e32 v[58:59], 0
	v_mov_b64_e32 v[60:61], 0
	v_mov_b64_e32 v[62:63], 0
	v_mov_b64_e32 v[64:65], 0
	v_mov_b64_e32 v[66:67], 0
	v_mov_b64_e32 v[68:69], 0
	v_mov_b64_e32 v[70:71], 0
	v_mov_b64_e32 v[72:73], 0
	v_mov_b64_e32 v[74:75], 0
	v_mov_b64_e32 v[76:77], 0
	v_mov_b64_e32 v[78:79], 0
	v_mov_b64_e32 v[80:81], 0
	v_mov_b64_e32 v[82:83], 0
	v_mov_b64_e32 v[84:85], 0
	v_mov_b64_e32 v[86:87], 0
	v_mov_b64_e32 v[88:89], 0
	v_mov_b64_e32 v[90:91], 0
	v_mov_b64_e32 v[92:93], 0
	v_mov_b64_e32 v[94:95], 0
	v_mov_b64_e32 v[96:97], 0
	v_mov_b64_e32 v[98:99], 0
	v_mov_b64_e32 v[100:101], 0
	v_mov_b64_e32 v[102:103], 0
	v_mov_b64_e32 v[104:105], 0
	v_mov_b64_e32 v[106:107], 0
	v_mov_b64_e32 v[108:109], 0
	v_mov_b64_e32 v[110:111], 0
	v_mov_b64_e32 v[112:113], 0
	v_mov_b64_e32 v[114:115], 0
	v_mov_b64_e32 v[116:117], 0
	v_mov_b64_e32 v[118:119], 0
	v_mov_b64_e32 v[120:121], 0
	v_mov_b64_e32 v[122:123], 0
	v_mov_b64_e32 v[124:125], 0
	v_mov_b64_e32 v[126:127], 0
	v_mov_b64_e32 v[128:129], 0
	s_addc_u32 s31, s1, 0
	s_mov_b32 s61, -2

.LBB0_2324:
	s_add_u32 s20, s36, 0x100
	v_mov_b64_e32 v[2:3], 0
	v_mov_b64_e32 v[4:5], 0
	v_mov_b64_e32 v[6:7], 0
	v_mov_b64_e32 v[8:9], 0
	v_mov_b64_e32 v[10:11], 0
	v_mov_b64_e32 v[12:13], 0
	v_mov_b64_e32 v[14:15], 0
	v_mov_b64_e32 v[16:17], 0
	v_mov_b64_e32 v[18:19], 0
	v_mov_b64_e32 v[20:21], 0
	v_mov_b64_e32 v[22:23], 0
	v_mov_b64_e32 v[24:25], 0
	v_mov_b64_e32 v[26:27], 0
	v_mov_b64_e32 v[28:29], 0
	v_mov_b64_e32 v[30:31], 0
	v_mov_b64_e32 v[32:33], 0
	v_mov_b64_e32 v[34:35], 0
	v_mov_b64_e32 v[36:37], 0
	v_mov_b64_e32 v[38:39], 0
	v_mov_b64_e32 v[40:41], 0
	v_mov_b64_e32 v[42:43], 0
	v_mov_b64_e32 v[44:45], 0
	v_mov_b64_e32 v[46:47], 0
	v_mov_b64_e32 v[48:49], 0
	v_mov_b64_e32 v[50:51], 0
	v_mov_b64_e32 v[52:53], 0
	v_mov_b64_e32 v[54:55], 0
	v_mov_b64_e32 v[56:57], 0
	v_mov_b64_e32 v[58:59], 0
	v_mov_b64_e32 v[60:61], 0
	v_mov_b64_e32 v[62:63], 0
	v_mov_b64_e32 v[64:65], 0
	v_mov_b64_e32 v[66:67], 0
	v_mov_b64_e32 v[68:69], 0
	v_mov_b64_e32 v[70:71], 0
	v_mov_b64_e32 v[72:73], 0
	v_mov_b64_e32 v[74:75], 0
	v_mov_b64_e32 v[76:77], 0
	v_mov_b64_e32 v[78:79], 0
	v_mov_b64_e32 v[80:81], 0
	v_mov_b64_e32 v[82:83], 0
	v_mov_b64_e32 v[84:85], 0
	v_mov_b64_e32 v[86:87], 0
	v_mov_b64_e32 v[88:89], 0
	v_mov_b64_e32 v[90:91], 0
	v_mov_b64_e32 v[92:93], 0
	v_mov_b64_e32 v[94:95], 0
	v_mov_b64_e32 v[96:97], 0
	v_mov_b64_e32 v[98:99], 0
	v_mov_b64_e32 v[100:101], 0
	v_mov_b64_e32 v[102:103], 0
	v_mov_b64_e32 v[104:105], 0
	v_mov_b64_e32 v[106:107], 0
	v_mov_b64_e32 v[108:109], 0
	v_mov_b64_e32 v[110:111], 0
	v_mov_b64_e32 v[112:113], 0
	v_mov_b64_e32 v[114:115], 0
	v_mov_b64_e32 v[116:117], 0
	v_mov_b64_e32 v[118:119], 0
	v_mov_b64_e32 v[120:121], 0
	v_mov_b64_e32 v[122:123], 0
	v_mov_b64_e32 v[124:125], 0
	v_mov_b64_e32 v[126:127], 0
	v_mov_b64_e32 v[128:129], 0
	s_addc_u32 s58, s37, 0
	s_mov_b32 s59, -2

.LBB0_2343:
	s_ashr_i32 s21, s20, 31
	s_lshl_b64 s[0:1], s[20:21], 17
	v_cmp_lt_i64_e32 vcc, s[22:23], v[138:139]
	s_add_u32 s22, s6, s0
	s_addc_u32 s23, s4, s1
	s_and_b64 s[0:1], vcc, exec
	s_cselect_b32 s21, s23, s31
	s_cselect_b32 s62, s22, s30
	s_ashr_i32 s19, s18, 31
	s_lshl_b64 s[0:1], s[18:19], 17
	s_add_u32 s24, s7, s0
	s_addc_u32 s25, s8, s1
	s_and_b64 s[0:1], vcc, exec
	v_mov_b64_e32 v[2:3], 0
	v_mov_b64_e32 v[4:5], 0
	v_mov_b64_e32 v[6:7], 0
	v_mov_b64_e32 v[8:9], 0
	v_mov_b64_e32 v[10:11], 0
	v_mov_b64_e32 v[12:13], 0
	v_mov_b64_e32 v[14:15], 0
	v_mov_b64_e32 v[16:17], 0
	v_mov_b64_e32 v[18:19], 0
	v_mov_b64_e32 v[20:21], 0
	v_mov_b64_e32 v[22:23], 0
	v_mov_b64_e32 v[24:25], 0
	v_mov_b64_e32 v[26:27], 0
	v_mov_b64_e32 v[28:29], 0
	v_mov_b64_e32 v[30:31], 0
	v_mov_b64_e32 v[32:33], 0
	v_mov_b64_e32 v[34:35], 0
	v_mov_b64_e32 v[36:37], 0
	v_mov_b64_e32 v[38:39], 0
	v_mov_b64_e32 v[40:41], 0
	v_mov_b64_e32 v[42:43], 0
	v_mov_b64_e32 v[44:45], 0
	v_mov_b64_e32 v[46:47], 0
	v_mov_b64_e32 v[48:49], 0
	v_mov_b64_e32 v[50:51], 0
	v_mov_b64_e32 v[52:53], 0
	v_mov_b64_e32 v[54:55], 0
	v_mov_b64_e32 v[56:57], 0
	v_mov_b64_e32 v[58:59], 0
	v_mov_b64_e32 v[60:61], 0
	v_mov_b64_e32 v[62:63], 0
	v_mov_b64_e32 v[64:65], 0
	v_mov_b64_e32 v[66:67], 0
	v_mov_b64_e32 v[68:69], 0
	v_mov_b64_e32 v[70:71], 0
	v_mov_b64_e32 v[72:73], 0
	v_mov_b64_e32 v[74:75], 0
	v_mov_b64_e32 v[76:77], 0
	v_mov_b64_e32 v[78:79], 0
	v_mov_b64_e32 v[80:81], 0
	v_mov_b64_e32 v[82:83], 0
	v_mov_b64_e32 v[84:85], 0
	v_mov_b64_e32 v[86:87], 0
	v_mov_b64_e32 v[88:89], 0
	v_mov_b64_e32 v[90:91], 0
	v_mov_b64_e32 v[92:93], 0
	v_mov_b64_e32 v[94:95], 0
	v_mov_b64_e32 v[96:97], 0
	v_mov_b64_e32 v[98:99], 0
	v_mov_b64_e32 v[100:101], 0
	v_mov_b64_e32 v[102:103], 0
	v_mov_b64_e32 v[104:105], 0
	v_mov_b64_e32 v[106:107], 0
	v_mov_b64_e32 v[108:109], 0
	v_mov_b64_e32 v[110:111], 0
	v_mov_b64_e32 v[112:113], 0
	v_mov_b64_e32 v[114:115], 0
	v_mov_b64_e32 v[116:117], 0
	v_mov_b64_e32 v[118:119], 0
	v_mov_b64_e32 v[120:121], 0
	v_mov_b64_e32 v[122:123], 0
	v_mov_b64_e32 v[124:125], 0
	v_mov_b64_e32 v[126:127], 0
	v_mov_b64_e32 v[128:129], 0
	s_cselect_b32 s19, s25, s29
	s_cselect_b32 s63, s24, s28
	s_mov_b32 s38, 0
	s_mov_b64 s[34:35], -1
	s_mov_b64 s[36:37], 0

.LBB0_2494:
	s_add_i32 s56, s56, 1
	s_mov_b64 s[0:1], s[24:25]
	s_lshr_b32 s24, s56, 2
	s_mul_i32 s24, s24, s74
	s_mov_b64 s[36:37], s[34:35]
	s_mov_b32 s35, s57
	s_add_i32 s57, s24, s2
	s_cmpk_lt_i32 s57, 0x100
	s_cselect_b64 s[38:39], -1, 0
	s_cmpk_gt_i32 s57, 0xff
	s_mov_b32 s34, s58
	s_cselect_b64 s[30:31], -1, 0
	s_and_b32 s58, s56, 3
	s_and_b64 s[24:25], s[38:39], exec
	s_cselect_b32 s24, s57, s35
	s_cselect_b32 s34, s58, s34
	s_ashr_i32 s25, s24, 31
	s_lshl_b64 s[24:25], s[24:25], 19
	s_add_u32 s24, s6, s24
	s_addc_u32 s25, s7, s25
	s_and_b64 s[40:41], s[38:39], exec
	s_cselect_b32 s61, s25, s1
	s_cselect_b32 s62, s24, s0
	s_ashr_i32 s35, s34, 31
	s_lshl_b64 s[34:35], s[34:35], 19
	s_add_u32 s34, s22, s34
	s_addc_u32 s35, s23, s35
	s_and_b64 s[38:39], s[38:39], exec
	s_cselect_b32 s63, s35, s37
	s_cselect_b32 s64, s34, s36
	s_add_u32 s65, s36, 0x100
	s_addc_u32 s67, s37, 0
	s_add_u32 s36, s0, 0x40080
	v_mov_b64_e32 v[2:3], 0
	v_mov_b64_e32 v[4:5], 0
	v_mov_b64_e32 v[6:7], 0
	v_mov_b64_e32 v[8:9], 0
	v_mov_b64_e32 v[10:11], 0
	v_mov_b64_e32 v[12:13], 0
	v_mov_b64_e32 v[14:15], 0
	v_mov_b64_e32 v[16:17], 0
	v_mov_b64_e32 v[18:19], 0
	v_mov_b64_e32 v[20:21], 0
	v_mov_b64_e32 v[22:23], 0
	v_mov_b64_e32 v[24:25], 0
	v_mov_b64_e32 v[26:27], 0
	v_mov_b64_e32 v[28:29], 0
	v_mov_b64_e32 v[30:31], 0
	v_mov_b64_e32 v[32:33], 0
	v_mov_b64_e32 v[34:35], 0
	v_mov_b64_e32 v[36:37], 0
	v_mov_b64_e32 v[38:39], 0
	v_mov_b64_e32 v[40:41], 0
	v_mov_b64_e32 v[42:43], 0
	v_mov_b64_e32 v[44:45], 0
	v_mov_b64_e32 v[46:47], 0
	v_mov_b64_e32 v[48:49], 0
	v_mov_b64_e32 v[50:51], 0
	v_mov_b64_e32 v[52:53], 0
	v_mov_b64_e32 v[54:55], 0
	v_mov_b64_e32 v[56:57], 0
	v_mov_b64_e32 v[58:59], 0
	v_mov_b64_e32 v[60:61], 0
	v_mov_b64_e32 v[62:63], 0
	v_mov_b64_e32 v[64:65], 0
	v_mov_b64_e32 v[66:67], 0
	v_mov_b64_e32 v[68:69], 0
	v_mov_b64_e32 v[70:71], 0
	v_mov_b64_e32 v[72:73], 0
	v_mov_b64_e32 v[74:75], 0
	v_mov_b64_e32 v[76:77], 0
	v_mov_b64_e32 v[78:79], 0
	v_mov_b64_e32 v[80:81], 0
	v_mov_b64_e32 v[82:83], 0
	v_mov_b64_e32 v[84:85], 0
	v_mov_b64_e32 v[86:87], 0
	v_mov_b64_e32 v[88:89], 0
	v_mov_b64_e32 v[90:91], 0
	v_mov_b64_e32 v[92:93], 0
	v_mov_b64_e32 v[94:95], 0
	v_mov_b64_e32 v[96:97], 0
	v_mov_b64_e32 v[98:99], 0
	v_mov_b64_e32 v[100:101], 0
	v_mov_b64_e32 v[102:103], 0
	v_mov_b64_e32 v[104:105], 0
	v_mov_b64_e32 v[106:107], 0
	v_mov_b64_e32 v[108:109], 0
	v_mov_b64_e32 v[110:111], 0
	v_mov_b64_e32 v[112:113], 0
	v_mov_b64_e32 v[114:115], 0
	v_mov_b64_e32 v[116:117], 0
	v_mov_b64_e32 v[118:119], 0
	v_mov_b64_e32 v[120:121], 0
	v_mov_b64_e32 v[122:123], 0
	v_mov_b64_e32 v[124:125], 0
	v_mov_b64_e32 v[126:127], 0
	v_mov_b64_e32 v[128:129], 0
	s_addc_u32 s37, s1, 0
	s_mov_b32 s69, -2

.LBB0_2815:
	s_ashr_i32 s19, s18, 31
	s_lshl_b64 s[0:1], s[18:19], 18
	v_cmp_lt_i64_e32 vcc, s[20:21], v[158:159]
	s_add_u32 s20, s5, s0
	s_addc_u32 s21, s8, s1
	s_and_b64 s[0:1], vcc, exec
	s_cselect_b32 s19, s21, s29
	s_cselect_b32 s49, s20, s28
	s_ashr_i32 s0, s18, 5
	s_ashr_i32 s1, s0, 31
	s_lshl_b64 s[0:1], s[0:1], 20
	s_add_u32 s22, s9, s0
	s_addc_u32 s23, s36, s1
	s_ashr_i32 s17, s16, 31
	s_lshl_b64 s[0:1], s[16:17], 18
	s_add_u32 s22, s22, s0
	s_addc_u32 s23, s23, s1
	s_and_b64 s[0:1], vcc, exec
	s_cselect_b32 s17, s23, s27
	s_cselect_b32 s50, s22, s26
	s_add_u32 s51, s26, 0x100
	s_addc_u32 s52, s27, 0
	s_add_u32 s26, s28, 0xc000
	v_mov_b64_e32 v[18:19], 0
	v_mov_b64_e32 v[20:21], 0
	v_mov_b64_e32 v[22:23], 0
	v_mov_b64_e32 v[24:25], 0
	v_mov_b64_e32 v[26:27], 0
	v_mov_b64_e32 v[28:29], 0
	v_mov_b64_e32 v[30:31], 0
	v_mov_b64_e32 v[32:33], 0
	v_mov_b64_e32 v[34:35], 0
	v_mov_b64_e32 v[36:37], 0
	v_mov_b64_e32 v[38:39], 0
	v_mov_b64_e32 v[40:41], 0
	v_mov_b64_e32 v[42:43], 0
	v_mov_b64_e32 v[44:45], 0
	v_mov_b64_e32 v[46:47], 0
	v_mov_b64_e32 v[48:49], 0
	v_mov_b64_e32 v[50:51], 0
	v_mov_b64_e32 v[52:53], 0
	v_mov_b64_e32 v[54:55], 0
	v_mov_b64_e32 v[56:57], 0
	v_mov_b64_e32 v[58:59], 0
	v_mov_b64_e32 v[60:61], 0
	v_mov_b64_e32 v[62:63], 0
	v_mov_b64_e32 v[64:65], 0
	v_mov_b64_e32 v[66:67], 0
	v_mov_b64_e32 v[68:69], 0
	v_mov_b64_e32 v[70:71], 0
	v_mov_b64_e32 v[72:73], 0
	v_mov_b64_e32 v[74:75], 0
	v_mov_b64_e32 v[76:77], 0
	v_mov_b64_e32 v[78:79], 0
	v_mov_b64_e32 v[80:81], 0
	v_mov_b64_e32 v[82:83], 0
	v_mov_b64_e32 v[84:85], 0
	v_mov_b64_e32 v[86:87], 0
	v_mov_b64_e32 v[88:89], 0
	v_mov_b64_e32 v[90:91], 0
	v_mov_b64_e32 v[92:93], 0
	v_mov_b64_e32 v[94:95], 0
	v_mov_b64_e32 v[96:97], 0
	v_mov_b64_e32 v[98:99], 0
	v_mov_b64_e32 v[100:101], 0
	v_mov_b64_e32 v[102:103], 0
	v_mov_b64_e32 v[104:105], 0
	v_mov_b64_e32 v[106:107], 0
	v_mov_b64_e32 v[108:109], 0
	v_mov_b64_e32 v[110:111], 0
	v_mov_b64_e32 v[112:113], 0
	v_mov_b64_e32 v[114:115], 0
	v_mov_b64_e32 v[116:117], 0
	v_mov_b64_e32 v[118:119], 0
	v_mov_b64_e32 v[120:121], 0
	v_mov_b64_e32 v[122:123], 0
	v_mov_b64_e32 v[124:125], 0
	v_mov_b64_e32 v[126:127], 0
	v_mov_b64_e32 v[128:129], 0
	v_mov_b64_e32 v[130:131], 0
	v_mov_b64_e32 v[132:133], 0
	v_mov_b64_e32 v[134:135], 0
	v_mov_b64_e32 v[136:137], 0
	v_mov_b64_e32 v[138:139], 0
	v_mov_b64_e32 v[140:141], 0
	v_mov_b64_e32 v[142:143], 0
	v_mov_b64_e32 v[144:145], 0
	s_addc_u32 s27, s29, 0
	s_mov_b32 s53, -2
